# prep stage 1: log-decay prefix sums via v_add_f32 with a DPP row_shr source instead of zero-fill + v_mov_b32_dpp + v_pk_add_f32 (same adds, 40 fewer instructions per item and wave)
# speedup vs baseline: 1.0056x; 1.0056x over previous
; __device__ __forceinline__ void phase_prep(const Params& p, unsigned char* shm) {
;     ...
;     auto zload = [&](int it) {
;         const int rw0 = (it >> 4) * 64;
; #pragma unroll
;         for (int i = 0; i < 6; ++i) { int grow = rw0 - 1 + zrow[i]; grow = grow < 0 ? 0 : grow; zpre[i] = *(const u32x4*)(p.Z + (size_t)grow * LDZ + ZC_S + zcol[i]); }
;     };
;     if ((int)blockIdx.x < NCH * 16) zload(blockIdx.x);
;     for (int item = blockIdx.x; item < NCH * 16; item += gridDim.x) {
;         int tid = threadIdx.x; asm volatile("" : "+v"(tid));
;         const int lane = tid & 63, wid = __builtin_amdgcn_readfirstlane(tid >> 6), fr = lane & 15, fq = lane >> 4;
;         const int h = item & 15, cidx = item >> 4, row0 = cidx * 64; const size_t chbase = (size_t)item * 4096;
;         const int crow = tid >> 3, cseg = (tid & 7) * 8;
;         {
;             const bool first = seq_first(row0);
; #pragma unroll
;             for (int i = 0; i < 6; ++i) {
;                 if (zlds[i] >= 0) {
;                     u32x4 v = zpre[i];
;                     if ((i == 0 || i == 2) && first && zrow[i] == 0) { v = (u32x4){0u, 0u, 0u, 0u};
;                         if (row0 >= MP) { const float* sp = p.st_shift + (size_t)((row0 - MP) >> 6) * NSHIFT + zcol[i]; const f32x4 a = *(const f32x4*)sp, b = *(const f32x4*)(sp + 4);
;                             v = (u32x4){pk_bf16(a[0], a[1]), pk_bf16(a[2], a[3]), pk_bf16(b[0], b[1]), pk_bf16(b[2], b[3])}; } }
;                     *(u32x4*)(shm + zlds[i]) = v; } }
;             const int nitem = item + (int)gridDim.x;
;             zload(nitem < NCH * 16 ? nitem : item);
;         }
;         LDS_BARRIER();
;         {
;             const int j = tid >> 3, p8 = tid & 7;
; #pragma unroll
;             for (int isa = 0; isa < 2; ++isa) {
;                 const int c = isa * 64 + 8 * p8;
;                 const u32x4 cu = *(const u32x4*)(zh + (j + 1) * LZH + c), pu = *(const u32x4*)(zh + j * LZH + c);
;                 const f32x4 m0 = *(const f32x4*)(prm + 512 + c), m1 = *(const f32x4*)(prm + 512 + c + 4);
;                 const unsigned cw[4] = {cu.x, cu.y, cu.z, cu.w}, pw[4] = {pu.x, pu.y, pu.z, pu.w};
;                 float x[8];
; #pragma unroll
;                 for (int e = 0; e < 4; ++e) { const float c0 = bf_lo(cw[e]), c1 = bf_hi(cw[e]), mA = e < 2 ? m0[2 * e] : m1[2 * e - 4], mB = e < 2 ? m0[2 * e + 1] : m1[2 * e - 3];
.LBB0_189:
	s_or_b64 exec, exec, s[18:19]
	s_add_i32 s70, s26, s38
	s_cmpk_gt_i32 s70, 0x21ff
	s_cselect_b64 s[42:43], -1, 0
	s_cmpk_lt_i32 s70, 0x2200
	s_cselect_b32 s18, s70, s26
	s_mov_b64 s[20:21], s[88:89]
	s_lshl_b32 s18, s18, 2
	s_andn2_b32 s18, s18, 63
	s_add_i32 s22, s18, -1
	v_add_u32_e32 v0, s22, v123
	v_max_i32_e32 v0, 0, v0
	s_mov_b64 s[18:19], s[90:91]
	s_waitcnt vmcnt(6) lgkmcnt(0)
	v_mov_b64_e32 v[8:9], s[20:21]
	v_mad_u64_u32 v[0:1], s[20:21], v0, s3, v[8:9]
	v_lshlrev_b32_e32 v126, 1, v122
	v_add_u32_e32 v2, s22, v176
	v_lshl_add_u64 v[0:1], v[0:1], 0, v[126:127]
	v_max_i32_e32 v2, 0, v2
	v_add_co_u32_e32 v0, vcc, s49, v0
	v_mad_u64_u32 v[2:3], s[20:21], v2, s3, v[8:9]
	v_mov_b32_e32 v137, v127
	v_addc_co_u32_e32 v1, vcc, 0, v1, vcc
	v_lshl_add_u64 v[2:3], v[2:3], 0, v[136:137]
	v_add_co_u32_e32 v2, vcc, s49, v2
	v_mov_b32_e32 v139, v127
	s_nop 0
	v_addc_co_u32_e32 v3, vcc, 0, v3, vcc
	global_load_dwordx4 v[20:23], v[0:1], off offset:2048
	global_load_dwordx4 v[16:19], v[2:3], off offset:2048
	v_add_u32_e32 v0, s22, v121
	v_max_i32_e32 v0, 0, v0
	v_mad_u64_u32 v[0:1], s[20:21], v0, s3, v[8:9]
	v_add_u32_e32 v2, s22, v175
	v_lshl_add_u64 v[0:1], v[124:125], 1, v[0:1]
	v_max_i32_e32 v2, 0, v2
	v_add_co_u32_e32 v0, vcc, s49, v0
	v_mad_u64_u32 v[2:3], s[20:21], v2, s3, v[8:9]
	v_add_u32_sdwa v10, s22, v157 dst_sel:DWORD dst_unused:UNUSED_PAD src0_sel:DWORD src1_sel:WORD_1
	v_addc_co_u32_e32 v1, vcc, 0, v1, vcc
	v_lshl_add_u64 v[2:3], v[2:3], 0, v[138:139]
	v_max_i32_e32 v10, 0, v10
	v_add_co_u32_e32 v2, vcc, s49, v2
	v_mad_u64_u32 v[10:11], s[20:21], v10, s3, v[8:9]
	v_mov_b32_e32 v141, v127
	v_add_u32_sdwa v12, s22, v174 dst_sel:DWORD dst_unused:UNUSED_PAD src0_sel:DWORD src1_sel:WORD_1
	v_addc_co_u32_e32 v3, vcc, 0, v3, vcc
	v_lshl_add_u64 v[10:11], v[10:11], 0, v[140:141]
	v_max_i32_e32 v12, 0, v12
	v_add_co_u32_e32 v10, vcc, s49, v10
	v_mad_u64_u32 v[8:9], s[20:21], v12, s3, v[8:9]
	v_mov_b32_e32 v143, v127
	v_lshlrev_b32_e32 v188, 3, v187
	v_addc_co_u32_e32 v11, vcc, 0, v11, vcc
	v_lshl_add_u64 v[8:9], v[8:9], 0, v[142:143]
	v_ashrrev_i32_e32 v186, 3, v187
	v_and_b32_e32 v32, 56, v188
	v_add_co_u32_e32 v8, vcc, s49, v8
	v_mul_lo_u32 v24, v186, s48
	s_nop 0
	v_addc_co_u32_e32 v9, vcc, 0, v9, vcc
	v_lshlrev_b32_e32 v144, 1, v32
	global_load_dwordx4 v[4:7], v[0:1], off offset:2048
	s_nop 0
	global_load_dwordx4 v[0:3], v[2:3], off offset:2048
	s_nop 0
	global_load_dwordx4 v[12:15], v[10:11], off offset:2048
	s_nop 0
	global_load_dwordx4 v[8:11], v[8:9], off offset:2048
	s_waitcnt lgkmcnt(0)
	s_barrier
	v_add3_u32 v45, 0, v24, v144
	ds_read_b128 v[24:27], v45 offset:37136
	ds_read_b128 v[28:31], v45 offset:36864
	v_lshlrev_b32_e32 v46, 2, v32
	v_add_u32_e32 v32, 0, v46
	v_add_u32_e32 v47, 0x25000, v32
	ds_read_b128 v[32:35], v47
	ds_read_b128 v[36:39], v47 offset:16
	s_waitcnt lgkmcnt(3)
	v_lshlrev_b32_e32 v40, 16, v24
	v_and_b32_e32 v41, 0xffff0000, v24
	s_waitcnt lgkmcnt(2)
	v_lshlrev_b32_e32 v42, 16, v28
	v_and_b32_e32 v43, 0xffff0000, v28
	v_lshlrev_b32_e32 v24, 16, v25
	v_and_b32_e32 v25, 0xffff0000, v25
	v_lshlrev_b32_e32 v28, 16, v29
	v_and_b32_e32 v29, 0xffff0000, v29
	v_pk_add_f32 v[28:29], v[28:29], v[24:25] neg_lo:[0,1] neg_hi:[0,1]
	v_pk_add_f32 v[42:43], v[42:43], v[40:41] neg_lo:[0,1] neg_hi:[0,1]
	s_waitcnt lgkmcnt(1)
	v_pk_fma_f32 v[24:25], v[34:35], v[28:29], v[24:25]
	v_lshlrev_b32_e32 v28, 16, v26
	v_and_b32_e32 v29, 0xffff0000, v26
	v_lshlrev_b32_e32 v34, 16, v30
	v_and_b32_e32 v35, 0xffff0000, v30
	v_lshlrev_b32_e32 v26, 16, v27
	v_and_b32_e32 v27, 0xffff0000, v27
	v_lshlrev_b32_e32 v30, 16, v31
	v_and_b32_e32 v31, 0xffff0000, v31
	v_pk_add_f32 v[34:35], v[34:35], v[28:29] neg_lo:[0,1] neg_hi:[0,1]
	v_pk_add_f32 v[30:31], v[30:31], v[26:27] neg_lo:[0,1] neg_hi:[0,1]
	v_pk_fma_f32 v[32:33], v[32:33], v[42:43], v[40:41]
	s_waitcnt lgkmcnt(0)
	v_pk_fma_f32 v[28:29], v[36:37], v[34:35], v[28:29]
	v_pk_fma_f32 v[26:27], v[38:39], v[30:31], v[26:27]
	v_pk_mul_f32 v[32:33], v[32:33], s[2:3] op_sel_hi:[1,0]
	v_pk_mul_f32 v[24:25], v[24:25], s[2:3] op_sel_hi:[1,0]
	v_pk_mul_f32 v[28:29], v[28:29], s[2:3] op_sel_hi:[1,0]
	v_pk_mul_f32 v[26:27], v[26:27], s[2:3] op_sel_hi:[1,0]
	v_exp_f32_e32 v32, v32
	v_exp_f32_e32 v33, v33
	v_exp_f32_e32 v24, v24
	v_exp_f32_e32 v25, v25
	v_exp_f32_e32 v28, v28
	v_exp_f32_e32 v29, v29
	v_exp_f32_e32 v26, v26
	v_exp_f32_e32 v27, v27
	v_pk_add_f32 v[32:33], v[32:33], 1.0 op_sel_hi:[1,0]
	v_pk_add_f32 v[24:25], v[24:25], 1.0 op_sel_hi:[1,0]
	v_pk_add_f32 v[28:29], v[28:29], 1.0 op_sel_hi:[1,0]
	v_pk_add_f32 v[26:27], v[26:27], 1.0 op_sel_hi:[1,0]
	v_rcp_f32_e32 v32, v32
	v_rcp_f32_e32 v33, v33
	v_rcp_f32_e32 v24, v24
	v_rcp_f32_e32 v25, v25
	v_rcp_f32_e32 v28, v28
	v_rcp_f32_e32 v29, v29
	v_rcp_f32_e32 v26, v26
	v_rcp_f32_e32 v27, v27
	v_mul_lo_u32 v44, v186, s50
	v_pk_fma_f32 v[30:31], v[32:33], 2.0, 1.0 op_sel_hi:[1,0,0] neg_lo:[1,0,0] neg_hi:[1,0,0]
	v_pk_fma_f32 v[32:33], v[24:25], 2.0, 1.0 op_sel_hi:[1,0,0] neg_lo:[1,0,0] neg_hi:[1,0,0]
	v_pk_fma_f32 v[28:29], v[28:29], 2.0, 1.0 op_sel_hi:[1,0,0] neg_lo:[1,0,0] neg_hi:[1,0,0]
	v_pk_fma_f32 v[34:35], v[26:27], 2.0, 1.0 op_sel_hi:[1,0,0] neg_lo:[1,0,0] neg_hi:[1,0,0]
	v_cvt_pk_bf16_f32 v24, v30, v31
	v_cvt_pk_bf16_f32 v25, v32, v33
	v_cvt_pk_bf16_f32 v26, v28, v29
	v_cvt_pk_bf16_f32 v27, v34, v35
	v_add3_u32 v44, 0, v44, v144
	ds_read_b128 v[28:31], v45 offset:37264
	ds_write_b128 v44, v[24:27]
	ds_read_b128 v[24:27], v45 offset:36992
	ds_read_b128 v[32:35], v47 offset:256
	ds_read_b128 v[36:39], v47 offset:272
	s_and_b32 s22, s26, 15
	s_lshl_b32 s40, s22, 7
	s_waitcnt lgkmcnt(4)
	v_lshlrev_b32_e32 v40, 16, v28
	v_and_b32_e32 v41, 0xffff0000, v28
	s_waitcnt lgkmcnt(2)
; __device__ __forceinline__ float bf_lo(unsigned u) { return __uint_as_float(u << 16); }
; __device__ __forceinline__ void phase_prep(const Params& p, unsigned char* shm) {
;     ...
;                 if (isa == 0) {
; #pragma unroll
;                     for (int e = 0; e < 4; ++e) { const f32x2 th = tanh2((f32x2){x[2 * e], x[2 * e + 1]}); x[2 * e] = th.x; x[2 * e + 1] = th.y; }
;                 }
;                 *(u32x4*)((isa ? tha : thw) + j * LD + 8 * p8) = (u32x4){pk_bf16(x[0], x[1]), pk_bf16(x[2], x[3]), pk_bf16(x[4], x[5]), pk_bf16(x[6], x[7])};
;             }
;             {
;                 const u32x4 cu = *(const u32x4*)(zs + (j + 1) * LZS + 128 + 8 * p8), pu = *(const u32x4*)(zs + j * LZS + 128 + 8 * p8);
;                 const f32x4 m0 = *(const f32x4*)(prm + 256 + 8 * p8), m1 = *(const f32x4*)(prm + 256 + 8 * p8 + 4);
;                 const unsigned cw[4] = {cu.x, cu.y, cu.z, cu.w}, pw[4] = {pu.x, pu.y, pu.z, pu.w};
;                 float x[8];
; #pragma unroll
;                 for (int e = 0; e < 4; ++e) { const float c0 = bf_lo(cw[e]), c1 = bf_hi(cw[e]), mA = e < 2 ? m0[2 * e] : m1[2 * e - 4], mB = e < 2 ? m0[2 * e + 1] : m1[2 * e - 3];
;                     x[2 * e] = c0 + mA * (bf_lo(pw[e]) - c0); x[2 * e + 1] = c1 + mB * (bf_hi(pw[e]) - c1); }
;                 *(u32x4*)(p.PV + ((size_t)(row0 + j) * 16 + h) * 64 + 8 * p8) = (u32x4){pk_bf16(x[0], x[1]), pk_bf16(x[2], x[3]), pk_bf16(x[4], x[5]), pk_bf16(x[6], x[7])};
;             }
;         }
;         LDS_BARRIER();
;         const int tt = wid & 3, chh = wid >> 2, tk = 16 * tt + fr, row = row0 + tk;
;         f32x4 lw[2], av[2], vm[2], kkv[2], kp[2], rm[2], cs[2]; float nrm = 0.f, rk = 0.f;
;         {
;             f32x4 accd[2], acca[2];
; #pragma unroll
;             for (int n = 0; n < 2; ++n) { accd[n] = (f32x4){0.f, 0.f, 0.f, 0.f}; acca[n] = (f32x4){0.f, 0.f, 0.f, 0.f}; }
; #pragma unroll
;             for (int ks = 0; ks < 2; ++ks) {
;                 const bf16x8 bw = ldfrag(thw, LD, 16 * tt, 32 * ks, fr, fq), ba = ldfrag(tha, LD, 16 * tt, 32 * ks, fr, fq);
; #pragma unroll
;                 for (int n = 0; n < 2; ++n) {
;                     accd[n] = MFMA16(ldfrag(w2P, LD, 32 * chh + 16 * n, 32 * ks, fr, fq), bw, accd[n]);
;                     acca[n] = MFMA16(ldfrag(a2P, LD, 32 * chh + 16 * n, 32 * ks, fr, fq), ba, acca[n]);
;                 }
;             }
	v_lshlrev_b32_e32 v42, 16, v24
	v_and_b32_e32 v43, 0xffff0000, v24
	v_lshlrev_b32_e32 v28, 16, v29
	v_and_b32_e32 v29, 0xffff0000, v29
	v_lshlrev_b32_e32 v24, 16, v25
	v_and_b32_e32 v25, 0xffff0000, v25
	v_pk_add_f32 v[24:25], v[24:25], v[28:29] neg_lo:[0,1] neg_hi:[0,1]
	v_pk_add_f32 v[42:43], v[42:43], v[40:41] neg_lo:[0,1] neg_hi:[0,1]
	s_waitcnt lgkmcnt(1)
	v_pk_fma_f32 v[28:29], v[34:35], v[24:25], v[28:29]
	v_lshlrev_b32_e32 v24, 16, v30
	v_and_b32_e32 v25, 0xffff0000, v30
	v_lshlrev_b32_e32 v34, 16, v26
	v_and_b32_e32 v35, 0xffff0000, v26
	v_pk_add_f32 v[34:35], v[34:35], v[24:25] neg_lo:[0,1] neg_hi:[0,1]
	v_lshlrev_b32_e32 v26, 16, v27
	s_waitcnt lgkmcnt(0)
	v_pk_fma_f32 v[34:35], v[36:37], v[34:35], v[24:25]
	v_lshlrev_b32_e32 v24, 16, v31
	v_and_b32_e32 v25, 0xffff0000, v31
	v_and_b32_e32 v27, 0xffff0000, v27
	v_pk_add_f32 v[26:27], v[26:27], v[24:25] neg_lo:[0,1] neg_hi:[0,1]
	v_pk_fma_f32 v[32:33], v[32:33], v[42:43], v[40:41]
	v_pk_fma_f32 v[30:31], v[38:39], v[26:27], v[24:25]
	v_cvt_pk_bf16_f32 v24, v32, v33
	v_cvt_pk_bf16_f32 v25, v28, v29
	v_cvt_pk_bf16_f32 v26, v34, v35
	v_cvt_pk_bf16_f32 v27, v30, v31
	ds_write_b128 v44, v[24:27] offset:9216
	v_mul_lo_u32 v24, v186, s51
	v_add3_u32 v28, 0, v24, v144
	ds_read_b128 v[24:27], v28 offset:55200
	ds_read_b128 v[28:31], v28 offset:54800
	v_add_u32_e32 v36, s52, v46
	ds_read_b128 v[32:35], v36
	ds_read_b128 v[36:39], v36 offset:16
	v_mov_b32_e32 v145, v127
	s_waitcnt lgkmcnt(3)
	v_lshlrev_b32_e32 v40, 16, v24
	v_and_b32_e32 v41, 0xffff0000, v24
	s_waitcnt lgkmcnt(2)
	v_lshlrev_b32_e32 v42, 16, v28
	v_and_b32_e32 v43, 0xffff0000, v28
	v_lshlrev_b32_e32 v24, 16, v25
	v_and_b32_e32 v25, 0xffff0000, v25
	v_lshlrev_b32_e32 v28, 16, v29
	v_and_b32_e32 v29, 0xffff0000, v29
	v_pk_add_f32 v[28:29], v[28:29], v[24:25] neg_lo:[0,1] neg_hi:[0,1]
	v_pk_add_f32 v[42:43], v[42:43], v[40:41] neg_lo:[0,1] neg_hi:[0,1]
	s_waitcnt lgkmcnt(1)
	v_pk_fma_f32 v[28:29], v[34:35], v[28:29], v[24:25]
	v_lshlrev_b32_e32 v24, 16, v26
	v_and_b32_e32 v25, 0xffff0000, v26
	v_lshlrev_b32_e32 v34, 16, v30
	v_and_b32_e32 v35, 0xffff0000, v30
	v_pk_add_f32 v[34:35], v[34:35], v[24:25] neg_lo:[0,1] neg_hi:[0,1]
	v_lshlrev_b32_e32 v26, 16, v31
	s_waitcnt lgkmcnt(0)
	v_pk_fma_f32 v[34:35], v[36:37], v[34:35], v[24:25]
	v_lshlrev_b32_e32 v24, 16, v27
	v_and_b32_e32 v25, 0xffff0000, v27
	v_and_b32_e32 v27, 0xffff0000, v31
	v_pk_add_f32 v[26:27], v[26:27], v[24:25] neg_lo:[0,1] neg_hi:[0,1]
	v_pk_fma_f32 v[32:33], v[32:33], v[42:43], v[40:41]
	v_pk_fma_f32 v[30:31], v[38:39], v[26:27], v[24:25]
	v_cvt_pk_bf16_f32 v25, v28, v29
	v_add_u32_e32 v28, s24, v186
	v_ashrrev_i32_e32 v29, 31, v28
	v_lshlrev_b64 v[28:29], 11, v[28:29]
	v_lshl_add_u64 v[28:29], s[18:19], 0, v[28:29]
	v_lshl_add_u64 v[28:29], v[28:29], 0, s[40:41]
	s_ashr_i32 s29, s25, 8
	v_and_b32_e32 v185, 15, v187
	v_cvt_pk_bf16_f32 v24, v32, v33
	v_cvt_pk_bf16_f32 v26, v34, v35
	v_cvt_pk_bf16_f32 v27, v30, v31
	v_lshl_add_u64 v[28:29], v[28:29], 0, v[144:145]
	s_lshl_b32 s18, s29, 5
	global_store_dwordx4 v[28:29], v[24:27], off
	v_and_b32_e32 v141, 48, v187
	s_waitcnt lgkmcnt(0)
	s_barrier
	v_or_b32_e32 v24, s18, v185
	v_mul_lo_u32 v145, v24, s50
	v_add3_u32 v60, s5, v141, v145
	s_bfe_u32 s28, s25, 0x20006
	ds_read_b128 v[24:27], v60
	v_lshl_or_b32 v126, s28, 4, v185
	v_mad_u32_u24 v143, v126, s50, 0
	v_add_u32_e32 v189, v143, v141
	v_add3_u32 v64, s7, v141, v145
	ds_read_b128 v[28:31], v189
	ds_read_b128 v[32:35], v64
	ds_read_b128 v[36:39], v189 offset:64
	ds_read_b128 v[40:43], v60 offset:64
	ds_read_b128 v[44:47], v189 offset:9216
	ds_read_b128 v[48:51], v189 offset:9280
	ds_read_b128 v[52:55], v64 offset:64
	ds_read_b128 v[56:59], v60 offset:2304
	ds_read_b128 v[60:63], v60 offset:2368
	s_waitcnt lgkmcnt(4)
	v_mfma_f32_16x16x32_bf16 v[32:35], v[32:35], v[44:47], 0
	v_bfe_u32 v137, v187, 4, 2
	v_lshlrev_b32_e32 v139, 2, v137
	v_or_b32_e32 v146, s18, v139
	v_mfma_f32_16x16x32_bf16 v[24:27], v[24:27], v[28:31], 0
	v_lshlrev_b32_e32 v147, 1, v146
	s_lshl_b32 s20, s28, 8
	s_add_i32 s20, s20, 0
	s_waitcnt lgkmcnt(1)
	v_mfma_f32_16x16x32_bf16 v[28:31], v[56:59], v[28:31], 0
	ds_read_b128 v[56:59], v64 offset:2304
	ds_read_b128 v[64:67], v64 offset:2368
	s_add_i32 s20, s20, 0x1b400
	v_cmp_eq_u32_e64 s[18:19], 15, v185
	v_mfma_f32_16x16x32_bf16 v[72:75], v[52:55], v[48:51], v[32:35]
	v_lshl_add_u32 v191, v146, 2, s20
	s_nop 1
	v_lshlrev_b32_e32 v34, 2, v146
	v_add_u32_e32 v35, 0, v34
	v_mfma_f32_16x16x32_bf16 v[40:43], v[40:43], v[36:39], v[24:27]
	v_add_u32_e32 v32, 0x24900, v35
	ds_read_b128 v[84:87], v32
	s_waitcnt lgkmcnt(3)
	v_mfma_f32_16x16x32_bf16 v[24:27], v[60:63], v[36:39], v[28:31]
	v_lshlrev_b32_e32 v36, 8, v126
	s_nop 1
	v_add_u32_e32 v28, 0x24800, v35
	ds_read_b128 v[28:31], v28
	s_waitcnt lgkmcnt(3)
	v_mfma_f32_16x16x32_bf16 v[44:47], v[56:59], v[44:47], 0
	s_waitcnt lgkmcnt(0)
; __device__ __forceinline__ f32x4 ld_bf4(const bf16_t* p) { const u32x2 u = *(const u32x2*)p; return (f32x4){bf_lo(u.x), bf_hi(u.x), bf_lo(u.y), bf_hi(u.y)}; }
; __device__ __forceinline__ void phase_prep(const Params& p, unsigned char* shm) {
;     ...
;                 const f32x4 d = *(const f32x4*)(prm + c4) + accd[n], al = *(const f32x4*)(prm + 64 + c4) + acca[n];
; { const f32x2 s0 = sigmoid2((f32x2){d[0], d[1]}), s1 = sigmoid2((f32x2){d[2], d[3]}), a0 = sigmoid2((f32x2){al[0], al[1]}), a1 = sigmoid2((f32x2){al[2], al[3]});
;                   lw[n] = (f32x4){s0.x, s0.y, s1.x, s1.y} * (-0.87503886f); av[n] = (f32x4){a0.x, a0.y, a1.x, a1.y}; }
;                 { const f32x4 vc = ld_bf4(zc + 128 + c4), vp = ld_bf4(zp + 128 + c4); vm[n] = vc + *(const f32x4*)(prm + 256 + c4) * (vp - vc); }
;                 const f32x4 kc = ld_bf4(zc + 64 + c4), kpv = ld_bf4(zp + 64 + c4);
;                 const f32x4 k = kc + *(const f32x4*)(prm + 192 + c4) * (kpv - kc);
;                 kkv[n] = k * *(const f32x4*)(prm + 320 + c4);
;                 kp[n] = k * (1.0f + (av[n] - 1.0f) * *(const f32x4*)(prm + 384 + c4));
;                 const f32x4 rc = ld_bf4(zc + c4), rp = ld_bf4(zp + c4);
;                 rm[n] = rc + *(const f32x4*)(prm + 128 + c4) * (rp - rc);
;                 const f32x4 rkw = rm[n] * kp[n] * *(const f32x4*)(prm + 448 + c4);
;                 { const f32x4 sq = kkv[n] * kkv[n]; nrm += (sq[0] + sq[1]) + (sq[2] + sq[3]); }
;                 rk += rkw[0] + rkw[1] + rkw[2] + rkw[3];
; #pragma unroll
;                 for (int j = 0; j < 4; ++j) {
;                     float x = lw[n][j];
;                     x += __int_as_float(__builtin_amdgcn_update_dpp(0, __float_as_int(x), 0x111, 0xf, 0xf, false));
;                     x += __int_as_float(__builtin_amdgcn_update_dpp(0, __float_as_int(x), 0x112, 0xf, 0xf, false));
;                     x += __int_as_float(__builtin_amdgcn_update_dpp(0, __float_as_int(x), 0x114, 0xf, 0xf, false));
;                     x += __int_as_float(__builtin_amdgcn_update_dpp(0, __float_as_int(x), 0x118, 0xf, 0xf, false));
;                     cs[n][j] = x;
;                 }
;                 if (fr == 15) *(f32x4*)(tot + tt * 64 + c4) = cs[n];
	v_pk_add_f32 v[28:29], v[40:41], v[28:29]
	s_nop 0
	v_pk_mul_f32 v[28:29], v[28:29], s[4:5] op_sel_hi:[1,0]
	v_pk_add_f32 v[30:31], v[42:43], v[30:31]
	v_exp_f32_e32 v28, v28
	v_exp_f32_e32 v29, v29
	v_mfma_f32_16x16x32_bf16 v[56:59], v[64:67], v[48:51], v[44:47]
	v_mul_f32_e64 v30, v30, s4
	v_mul_f32_e64 v31, v31, s4
	v_pk_add_f32 v[28:29], v[28:29], 1.0 op_sel_hi:[1,0]
	s_nop 0
	v_rcp_f32_e32 v32, v28
	v_rcp_f32_e32 v33, v29
	v_add3_u32 v28, v143, v36, v147
	v_add_u32_e32 v28, 0xd000, v28
	v_add_u32_e32 v29, s52, v34
	v_add_u32_e32 v34, 0x24b00, v35
	ds_read2_b64 v[52:55], v28 offset0:228 offset1:244
	ds_read2_b64 v[48:51], v28 offset0:194 offset1:212
	ds_read2_b64 v[68:71], v28 offset0:162 offset1:178
	ds_read_b128 v[44:47], v29
	ds_read_b128 v[92:95], v34
	v_add_u32_e32 v29, 0x24d00, v35
	v_add_u32_e32 v34, 0x24e00, v35
	v_exp_f32_e32 v30, v30
	v_exp_f32_e32 v31, v31
	ds_read_b128 v[96:99], v29
	ds_read_b128 v[76:79], v34
	v_add_u32_e32 v29, 0x24a00, v35
	v_add_u32_e32 v34, 0x24f00, v35
	v_pk_mul_f32 v[154:155], v[32:33], s[6:7] op_sel_hi:[1,0]
	ds_read_b128 v[64:67], v29
	ds_read_b128 v[60:63], v34
	v_mov_b32_e32 v34, v127
	v_mov_b32_e32 v35, v127
	v_pk_add_f32 v[30:31], v[30:31], 1.0 op_sel_hi:[1,0]
	v_mov_b32_dpp v34, v154 row_shr:1 row_mask:0xf bank_mask:0xf
	v_mov_b32_dpp v35, v155 row_shr:1 row_mask:0xf bank_mask:0xf
	v_pk_fma_f32 v[32:33], v[32:33], s[6:7], v[34:35] op_sel_hi:[1,0,1]
	v_rcp_f32_e32 v30, v30
	v_rcp_f32_e32 v31, v31
	v_add_f32_dpp v32, v32, v32 row_shr:2 row_mask:0xf bank_mask:0xf bound_ctrl:1
	v_add_f32_dpp v33, v33, v33 row_shr:2 row_mask:0xf bank_mask:0xf bound_ctrl:1
	v_pk_mul_f32 v[152:153], v[30:31], s[6:7] op_sel_hi:[1,0]
	v_mov_b32_e32 v34, v127
	v_mov_b32_e32 v35, v127
	v_add_f32_dpp v32, v32, v32 row_shr:4 row_mask:0xf bank_mask:0xf bound_ctrl:1
	v_add_f32_dpp v33, v33, v33 row_shr:4 row_mask:0xf bank_mask:0xf bound_ctrl:1
	v_mov_b32_dpp v34, v152 row_shr:1 row_mask:0xf bank_mask:0xf
	v_mov_b32_dpp v35, v153 row_shr:1 row_mask:0xf bank_mask:0xf
	v_add_f32_dpp v40, v32, v32 row_shr:8 row_mask:0xf bank_mask:0xf bound_ctrl:1
	v_add_f32_dpp v41, v33, v33 row_shr:8 row_mask:0xf bank_mask:0xf bound_ctrl:1
	v_pk_fma_f32 v[30:31], v[30:31], s[6:7], v[34:35] op_sel_hi:[1,0,1]
	s_nop 1
	v_add_f32_dpp v30, v30, v30 row_shr:2 row_mask:0xf bank_mask:0xf bound_ctrl:1
	v_add_f32_dpp v31, v31, v31 row_shr:2 row_mask:0xf bank_mask:0xf bound_ctrl:1
	s_nop 0
	v_add_f32_dpp v30, v30, v30 row_shr:4 row_mask:0xf bank_mask:0xf bound_ctrl:1
	v_add_f32_dpp v31, v31, v31 row_shr:4 row_mask:0xf bank_mask:0xf bound_ctrl:1
	s_nop 0
	v_add_f32_dpp v42, v30, v30 row_shr:8 row_mask:0xf bank_mask:0xf bound_ctrl:1
	v_add_f32_dpp v43, v31, v31 row_shr:8 row_mask:0xf bank_mask:0xf bound_ctrl:1
	s_and_saveexec_b64 s[20:21], s[18:19]
	ds_write_b128 v191, v[40:43]
	s_or_b64 exec, exec, s[20:21]
	v_or_b32_e32 v29, 16, v146
	v_lshl_add_u32 v190, v29, 2, 0
	v_add_u32_e32 v29, 0x24800, v190
	ds_read_b128 v[30:33], v29
	v_mov_b32_e32 v196, v127
	v_mov_b32_e32 v197, v127
	v_add_u32_e32 v29, 0x24900, v190
	ds_read_b128 v[116:119], v29
	s_waitcnt lgkmcnt(1)
	v_pk_add_f32 v[24:25], v[24:25], v[30:31]
	v_pk_add_f32 v[26:27], v[26:27], v[32:33]
	v_pk_mul_f32 v[24:25], v[24:25], s[4:5] op_sel_hi:[1,0]
	v_pk_mul_f32 v[26:27], v[26:27], s[4:5] op_sel_hi:[1,0]
	v_exp_f32_e32 v24, v24
	v_exp_f32_e32 v25, v25
	v_exp_f32_e32 v26, v26
	v_exp_f32_e32 v27, v27
	v_add_u32_e32 v29, 0x24c00, v190
	v_pk_add_f32 v[24:25], v[24:25], 1.0 op_sel_hi:[1,0]
	v_add_u32_e32 v80, 0x24b00, v190
	v_rcp_f32_e32 v24, v24
	v_rcp_f32_e32 v25, v25
	v_pk_add_f32 v[26:27], v[26:27], 1.0 op_sel_hi:[1,0]
	ds_read2_b64 v[36:39], v28 offset0:232 offset1:248
	ds_read2_b64 v[32:35], v28 offset0:198 offset1:216
	v_rcp_f32_e32 v26, v26
	v_pk_mul_f32 v[150:151], v[24:25], s[6:7] op_sel_hi:[1,0]
	v_rcp_f32_e32 v27, v27
	ds_read2_b64 v[100:103], v28 offset0:166 offset1:182
	v_mov_b32_dpp v196, v150 row_shr:1 row_mask:0xf bank_mask:0xf
	v_mov_b32_dpp v197, v151 row_shr:1 row_mask:0xf bank_mask:0xf
	v_pk_fma_f32 v[24:25], v[24:25], s[6:7], v[196:197] op_sel_hi:[1,0,1]
	v_mov_b32_e32 v196, v127
	v_mov_b32_e32 v197, v127
	v_pk_mul_f32 v[148:149], v[26:27], s[6:7] op_sel_hi:[1,0]
	v_add_f32_dpp v24, v24, v24 row_shr:2 row_mask:0xf bank_mask:0xf bound_ctrl:1
	v_add_f32_dpp v25, v25, v25 row_shr:2 row_mask:0xf bank_mask:0xf bound_ctrl:1
	ds_read_b128 v[28:31], v29
	ds_read_b128 v[108:111], v80
	v_add_f32_dpp v24, v24, v24 row_shr:4 row_mask:0xf bank_mask:0xf bound_ctrl:1
	v_add_f32_dpp v25, v25, v25 row_shr:4 row_mask:0xf bank_mask:0xf bound_ctrl:1
	v_add_u32_e32 v80, 0x24d00, v190
	v_mov_b32_dpp v196, v148 row_shr:1 row_mask:0xf bank_mask:0xf
	v_mov_b32_dpp v197, v149 row_shr:1 row_mask:0xf bank_mask:0xf
	v_add_f32_dpp v24, v24, v24 row_shr:8 row_mask:0xf bank_mask:0xf bound_ctrl:1
	v_add_f32_dpp v25, v25, v25 row_shr:8 row_mask:0xf bank_mask:0xf bound_ctrl:1
	v_add_u32_e32 v81, 0x24e00, v190
	v_pk_fma_f32 v[26:27], v[26:27], s[6:7], v[196:197] op_sel_hi:[1,0,1]
	ds_read_b128 v[112:115], v80
	ds_read_b128 v[104:107], v81
	v_add_u32_e32 v80, 0x24a00, v190
	v_add_u32_e32 v81, 0x24f00, v190
	v_add_f32_dpp v26, v26, v26 row_shr:2 row_mask:0xf bank_mask:0xf bound_ctrl:1
	v_add_f32_dpp v27, v27, v27 row_shr:2 row_mask:0xf bank_mask:0xf bound_ctrl:1
	ds_read_b128 v[88:91], v80
	ds_read_b128 v[80:83], v81
	v_add_f32_dpp v26, v26, v26 row_shr:4 row_mask:0xf bank_mask:0xf bound_ctrl:1
	v_add_f32_dpp v27, v27, v27 row_shr:4 row_mask:0xf bank_mask:0xf bound_ctrl:1
	s_nop 0
	v_add_f32_dpp v26, v26, v26 row_shr:8 row_mask:0xf bank_mask:0xf bound_ctrl:1
	v_add_f32_dpp v27, v27, v27 row_shr:8 row_mask:0xf bank_mask:0xf bound_ctrl:1
; __device__ __forceinline__ f32x4 ld_bf4(const bf16_t* p) { const u32x2 u = *(const u32x2*)p; return (f32x4){bf_lo(u.x), bf_hi(u.x), bf_lo(u.y), bf_hi(u.y)}; }
; #define LDS_BARRIER() do { asm volatile("s_waitcnt lgkmcnt(0)" ::: "memory"); __builtin_amdgcn_s_barrier(); asm volatile("" ::: "memory"); } while (0)
; __device__ __forceinline__ void phase_prep(const Params& p, unsigned char* shm) {
;     ...
;                 { const f32x4 vc = ld_bf4(zc + 128 + c4), vp = ld_bf4(zp + 128 + c4); vm[n] = vc + *(const f32x4*)(prm + 256 + c4) * (vp - vc); }
;                 const f32x4 kc = ld_bf4(zc + 64 + c4), kpv = ld_bf4(zp + 64 + c4);
;                 const f32x4 k = kc + *(const f32x4*)(prm + 192 + c4) * (kpv - kc);
;                 kkv[n] = k * *(const f32x4*)(prm + 320 + c4);
;                 kp[n] = k * (1.0f + (av[n] - 1.0f) * *(const f32x4*)(prm + 384 + c4));
;                 const f32x4 rc = ld_bf4(zc + c4), rp = ld_bf4(zp + c4);
;                 rm[n] = rc + *(const f32x4*)(prm + 128 + c4) * (rp - rc);
;                 const f32x4 rkw = rm[n] * kp[n] * *(const f32x4*)(prm + 448 + c4);
;                 { const f32x4 sq = kkv[n] * kkv[n]; nrm += (sq[0] + sq[1]) + (sq[2] + sq[3]); }
;                 rk += rkw[0] + rkw[1] + rkw[2] + rkw[3];
; #pragma unroll
;                 for (int j = 0; j < 4; ++j) {
;                     float x = lw[n][j];
;                     x += __int_as_float(__builtin_amdgcn_update_dpp(0, __float_as_int(x), 0x111, 0xf, 0xf, false));
;                     x += __int_as_float(__builtin_amdgcn_update_dpp(0, __float_as_int(x), 0x112, 0xf, 0xf, false));
;                     x += __int_as_float(__builtin_amdgcn_update_dpp(0, __float_as_int(x), 0x114, 0xf, 0xf, false));
;                     x += __int_as_float(__builtin_amdgcn_update_dpp(0, __float_as_int(x), 0x118, 0xf, 0xf, false));
;                     cs[n][j] = x;
;                 }
;                 if (fr == 15) *(f32x4*)(tot + tt * 64 + c4) = cs[n];
;             }
;             nrm += __shfl_xor(nrm, 16); nrm += __shfl_xor(nrm, 32);
;             rk += __shfl_xor(rk, 16); rk += __shfl_xor(rk, 32);
;             if (fq == 0) { red[wid * 16 + fr] = nrm; red[128 + wid * 16 + fr] = rk; }
;         }
;         LDS_BARRIER();
	s_and_saveexec_b64 s[20:21], s[18:19]
	ds_write_b128 v191, v[24:27] offset:64
	s_or_b64 exec, exec, s[20:21]
	v_pk_add_f32 v[74:75], v[74:75], v[86:87]
	v_pk_add_f32 v[72:73], v[72:73], v[84:85]
	v_pk_mul_f32 v[74:75], v[74:75], s[4:5] op_sel_hi:[1,0]
	v_pk_mul_f32 v[72:73], v[72:73], s[4:5] op_sel_hi:[1,0]
	v_exp_f32_e32 v74, v74
	v_exp_f32_e32 v75, v75
	v_exp_f32_e32 v72, v72
	v_exp_f32_e32 v73, v73
	v_lshlrev_b32_e32 v84, 16, v52
	v_pk_add_f32 v[74:75], v[74:75], 1.0 op_sel_hi:[1,0]
	v_and_b32_e32 v85, 0xffff0000, v52
	v_pk_add_f32 v[72:73], v[72:73], 1.0 op_sel_hi:[1,0]
	v_rcp_f32_e32 v74, v74
	v_rcp_f32_e32 v75, v75
	v_rcp_f32_e32 v72, v72
	v_rcp_f32_e32 v73, v73
	v_lshlrev_b32_e32 v52, 16, v53
	v_and_b32_e32 v53, 0xffff0000, v53
	v_lshlrev_b32_e32 v86, 16, v70
	v_and_b32_e32 v87, 0xffff0000, v70
	v_lshlrev_b32_e32 v70, 16, v71
	v_and_b32_e32 v71, 0xffff0000, v71
	v_sub_f32_e32 v71, v71, v53
	v_sub_f32_e32 v70, v70, v52
	v_pk_fma_f32 v[52:53], v[94:95], v[70:71], v[52:53]
	v_pk_add_f32 v[94:95], v[74:75], -1.0 op_sel_hi:[1,0]
	v_sub_f32_e32 v87, v87, v85
	v_sub_f32_e32 v86, v86, v84
	v_pk_add_f32 v[70:71], v[72:73], -1.0 op_sel_hi:[1,0]
	v_pk_fma_f32 v[78:79], v[78:79], v[94:95], 1.0 op_sel_hi:[1,1,0]
	v_pk_fma_f32 v[92:93], v[92:93], v[86:87], v[84:85]
	v_pk_mul_f32 v[84:85], v[98:99], v[52:53]
	v_pk_fma_f32 v[70:71], v[76:77], v[70:71], 1.0 op_sel_hi:[1,1,0]
	v_pk_mul_f32 v[76:77], v[52:53], v[78:79]
	v_lshlrev_b32_e32 v52, 16, v50
	v_and_b32_e32 v53, 0xffff0000, v50
	v_lshlrev_b32_e32 v78, 16, v68
	v_and_b32_e32 v68, 0xffff0000, v68
	v_pk_mul_f32 v[86:87], v[96:97], v[92:93]
	v_pk_mul_f32 v[70:71], v[92:93], v[70:71]
	v_lshlrev_b32_e32 v50, 16, v51
	v_and_b32_e32 v51, 0xffff0000, v51
	v_lshlrev_b32_e32 v92, 16, v69
	v_and_b32_e32 v79, 0xffff0000, v69
	v_sub_f32_e32 v69, v68, v53
	v_sub_f32_e32 v68, v78, v52
	v_sub_f32_e32 v79, v79, v51
	v_sub_f32_e32 v78, v92, v50
	v_pk_fma_f32 v[64:65], v[64:65], v[68:69], v[52:53]
	v_pk_fma_f32 v[66:67], v[66:67], v[78:79], v[50:51]
	v_pk_mul_f32 v[50:51], v[70:71], v[64:65]
	v_pk_mul_f32 v[52:53], v[76:77], v[66:67]
	v_pk_mul_f32 v[50:51], v[60:61], v[50:51]
	v_pk_mul_f32 v[52:53], v[62:63], v[52:53]
	v_add_f32_e32 v50, v50, v51
	v_add_f32_e32 v50, v52, v50
	v_add_f32_e32 v50, v53, v50
	v_add_f32_e32 v93, 0, v50
	s_waitcnt lgkmcnt(9)
	v_pk_add_f32 v[50:51], v[58:59], v[118:119]
	v_pk_add_f32 v[52:53], v[56:57], v[116:117]
	v_pk_mul_f32 v[50:51], v[50:51], s[4:5] op_sel_hi:[1,0]
	v_pk_mul_f32 v[52:53], v[52:53], s[4:5] op_sel_hi:[1,0]
	v_exp_f32_e32 v56, v50
	v_exp_f32_e32 v52, v52
	v_exp_f32_e32 v53, v53
	v_exp_f32_e32 v57, v51
	v_pk_mul_f32 v[60:61], v[84:85], v[84:85]
	v_pk_mul_f32 v[62:63], v[86:87], v[86:87]
	v_pk_add_f32 v[50:51], v[52:53], 1.0 op_sel_hi:[1,0]
	v_pk_add_f32 v[52:53], v[56:57], 1.0 op_sel_hi:[1,0]
	v_rcp_f32_e32 v50, v50
	v_rcp_f32_e32 v51, v51
	v_rcp_f32_e32 v52, v52
	v_rcp_f32_e32 v53, v53
	v_add_f32_e32 v62, v62, v63
	v_add_f32_e32 v60, v60, v61
	s_waitcnt lgkmcnt(8)
	v_lshlrev_b32_e32 v56, 16, v36
	v_and_b32_e32 v57, 0xffff0000, v36
	v_lshlrev_b32_e32 v36, 16, v37
	v_and_b32_e32 v37, 0xffff0000, v37
	s_waitcnt lgkmcnt(6)
	v_lshlrev_b32_e32 v58, 16, v103
	v_and_b32_e32 v59, 0xffff0000, v103
	v_add_f32_e32 v92, v62, v60
	v_lshlrev_b32_e32 v60, 16, v102
	v_and_b32_e32 v61, 0xffff0000, v102
	v_sub_f32_e32 v59, v59, v37
	v_sub_f32_e32 v58, v58, v36
	v_sub_f32_e32 v61, v61, v57
	v_sub_f32_e32 v60, v60, v56
	s_waitcnt lgkmcnt(4)
	v_pk_fma_f32 v[62:63], v[110:111], v[58:59], v[36:37]
	v_pk_add_f32 v[36:37], v[50:51], -1.0 op_sel_hi:[1,0]
	v_pk_add_f32 v[68:69], v[52:53], -1.0 op_sel_hi:[1,0]
	v_pk_fma_f32 v[56:57], v[108:109], v[60:61], v[56:57]
	s_waitcnt lgkmcnt(2)
	v_pk_fma_f32 v[68:69], v[106:107], v[68:69], 1.0 op_sel_hi:[1,1,0]
	v_pk_fma_f32 v[36:37], v[104:105], v[36:37], 1.0 op_sel_hi:[1,1,0]
	v_pk_mul_f32 v[58:59], v[114:115], v[62:63]
	v_pk_mul_f32 v[60:61], v[112:113], v[56:57]
	v_pk_mul_f32 v[36:37], v[56:57], v[36:37]
	v_pk_mul_f32 v[56:57], v[62:63], v[68:69]
	v_lshlrev_b32_e32 v62, 16, v34
	v_and_b32_e32 v63, 0xffff0000, v34
	v_lshlrev_b32_e32 v34, 16, v35
	v_and_b32_e32 v35, 0xffff0000, v35
	v_lshlrev_b32_e32 v68, 16, v100
	v_and_b32_e32 v69, 0xffff0000, v100
	v_lshlrev_b32_e32 v78, 16, v101
	v_and_b32_e32 v79, 0xffff0000, v101
	v_sub_f32_e32 v69, v69, v63
	v_sub_f32_e32 v68, v68, v62
	v_sub_f32_e32 v79, v79, v35
	v_sub_f32_e32 v78, v78, v34
	s_waitcnt lgkmcnt(1)
	v_pk_fma_f32 v[34:35], v[90:91], v[78:79], v[34:35]
	v_pk_fma_f32 v[62:63], v[88:89], v[68:69], v[62:63]
	v_pk_mul_f32 v[78:79], v[56:57], v[34:35]
	v_pk_mul_f32 v[68:69], v[36:37], v[62:63]
	s_waitcnt lgkmcnt(0)
	v_pk_mul_f32 v[78:79], v[82:83], v[78:79]
	v_pk_mul_f32 v[68:69], v[80:81], v[68:69]
	v_pk_mul_f32 v[80:81], v[58:59], v[58:59]
	v_pk_mul_f32 v[82:83], v[60:61], v[60:61]
	v_add_f32_e32 v80, v80, v81
	v_add_f32_e32 v82, v82, v83
	v_add_f32_e32 v80, v82, v80
	v_and_b32_e32 v82, 64, v180
	v_xor_b32_e32 v81, 16, v180
	v_add_u32_e32 v82, 64, v82
	v_add_f32_e32 v68, v68, v69
	v_cmp_lt_i32_e32 vcc, v81, v82
	v_add_f32_e32 v68, v78, v68
	v_add_f32_e32 v68, v79, v68
	v_cndmask_b32_e32 v81, v180, v81, vcc
	v_add_f32_e32 v80, v92, v80
	v_lshlrev_b32_e32 v81, 2, v81
	v_add_f32_e32 v68, v93, v68
	ds_bpermute_b32 v83, v81, v80
	ds_bpermute_b32 v79, v81, v68
	v_xor_b32_e32 v78, 32, v180
	v_cmp_lt_i32_e32 vcc, v78, v82
	s_ashr_i32 s71, s25, 6
	s_waitcnt lgkmcnt(1)
	v_add_f32_e32 v69, v80, v83
	v_cndmask_b32_e32 v78, v180, v78, vcc
	v_lshlrev_b32_e32 v78, 2, v78
	s_waitcnt lgkmcnt(0)
	v_add_f32_e32 v79, v68, v79
	ds_bpermute_b32 v80, v78, v69
	ds_bpermute_b32 v81, v78, v79
	v_and_b32_e32 v68, 63, v187
	s_ashr_i32 s27, s26, 31
	v_cmp_gt_u32_e32 vcc, 16, v68
	s_waitcnt lgkmcnt(1)
	v_add_f32_e32 v78, v69, v80
	s_waitcnt lgkmcnt(0)
	v_add_f32_e32 v69, v79, v81
	s_lshl_b32 s72, s71, 4
	s_and_saveexec_b64 s[20:21], vcc
	s_lshl_b32 s23, s72, 2
	s_add_i32 s23, s23, 0
	v_lshl_add_u32 v79, v185, 2, s23
	v_add_u32_e32 v79, 0x1b000, v79
	ds_write2st64_b32 v79, v78, v69 offset1:2
	s_or_b64 exec, exec, s[20:21]
	s_xor_b32 s20, s72, 64
	s_lshl_b32 s20, s20, 2
	s_add_i32 s20, s20, 0
	v_lshl_add_u32 v81, v185, 2, s20
	s_waitcnt lgkmcnt(0)
	s_barrier
; __device__ __forceinline__ void st_bf4(bf16_t* p, f32x4 v) { u32x2 u; u.x = pk_bf16(v[0], v[1]); u.y = pk_bf16(v[2], v[3]); *(u32x2*)p = u; }
; __device__ __forceinline__ void phase_prep(const Params& p, unsigned char* shm) {
;     ...
;             nrm += red[(wid ^ 4) * 16 + fr]; rk += red[128 + (wid ^ 4) * 16 + fr];
;             const float inv = 1.0f / fmaxf(sqrtf(nrm), 1e-12f);
;             p.PRK[(size_t)row * 16 + h] = rk;
; #pragma unroll
;             for (int n = 0; n < 2; ++n) {
;                 const int c4 = 32 * chh + 16 * n + 4 * fq;
;                 f32x4 pre = (f32x4){0.f, 0.f, 0.f, 0.f}, total = (f32x4){0.f, 0.f, 0.f, 0.f};
; #pragma unroll
;                 for (int t2 = 0; t2 < 4; ++t2) { const f32x4 x = *(const f32x4*)(tot + t2 * 64 + c4); total += x; if (t2 < tt) pre += x; }
;                 const f32x4 csum = pre + cs[n];
;                 f32x4 eg, eng, egm, etc; const f32x4 ncs = -csum, cml = csum - lw[n], tmc = total - csum;
; #pragma unroll
;                 for (int j = 0; j < 4; ++j) { eg[j] = __builtin_amdgcn_exp2f(csum[j]); eng[j] = __builtin_amdgcn_exp2f(ncs[j]); egm[j] = __builtin_amdgcn_exp2f(cml[j]); etc[j] = __builtin_amdgcn_exp2f(tmc[j]); }
;                 const f32x4 kkn = kkv[n] * inv, bb = kkn * av[n];
;                 const f32x4 qt = rm[n] * eg, kt = kp[n] * eng, bt = bb * eng, kkt = kkn * egm, kpp = kp[n] * etc, bpp = bb * etc;
;                 st_bf4(Qt + tk * LD + c4, qt); st_bf4(Kt + tk * LD + c4, kt); st_bf4(Bt + tk * LD + c4, bt);
;                 const u32x2 kkw = pk_bf4(kkt), vmw = pk_bf4(vm[n]), kpw = pk_bf4(kpp), bpw = pk_bf4(bpp);
;                 *(u32x2*)(KKt + tk * LD + c4) = kkw;
;                 { bf16_t* d = KKtT + c4 * LD + tk; d[0] = (bf16_t)kkw.x; d[LD] = (bf16_t)(kkw.x >> 16); d[2 * LD] = (bf16_t)kkw.y; d[3 * LD] = (bf16_t)(kkw.y >> 16); }
;                 { bf16_t* d = VmT + c4 * LD + tk; d[0] = (bf16_t)vmw.x; d[LD] = (bf16_t)(vmw.x >> 16); d[2 * LD] = (bf16_t)vmw.y; d[3 * LD] = (bf16_t)(vmw.y >> 16); }
;                 { bf16_t* d = KpT + c4 * LD + tk; d[0] = (bf16_t)kpw.x; d[LD] = (bf16_t)(kpw.x >> 16); d[2 * LD] = (bf16_t)kpw.y; d[3 * LD] = (bf16_t)(kpw.y >> 16); }
;                 { bf16_t* d = BpT + c4 * LD + tk; d[0] = (bf16_t)bpw.x; d[LD] = (bf16_t)(bpw.x >> 16); d[2 * LD] = (bf16_t)bpw.y; d[3 * LD] = (bf16_t)(bpw.y >> 16); }
	v_add_u32_e32 v81, 0x1b000, v81
	ds_read2st64_b32 v[88:89], v81 offset1:2
	v_and_b32_e32 v83, 0xffff0000, v54
	v_lshlrev_b32_e32 v79, 16, v48
	v_and_b32_e32 v48, 0xffff0000, v48
	v_lshlrev_b32_e32 v81, 16, v49
	v_and_b32_e32 v90, 0xffff0000, v49
	v_sub_f32_e32 v49, v48, v83
	s_waitcnt lgkmcnt(0)
	v_add_f32_e32 v48, v78, v88
	v_mul_f32_e32 v78, 0x4f800000, v48
	v_cmp_gt_f32_e32 vcc, s53, v48
	v_lshlrev_b32_e32 v82, 16, v54
	v_lshlrev_b32_e32 v54, 16, v55
	v_cndmask_b32_e32 v88, v48, v78, vcc
	v_sqrt_f32_e32 v91, v88
	v_and_b32_e32 v55, 0xffff0000, v55
	v_sub_f32_e32 v78, v81, v54
	v_sub_f32_e32 v48, v79, v82
	v_add_u32_e32 v81, -1, v91
	v_sub_f32_e32 v79, v90, v55
	v_fma_f32 v90, -v81, v91, v88
	v_cmp_ge_f32_e64 s[20:21], 0, v90
	v_add_u32_e32 v90, 1, v91
	v_pk_fma_f32 v[82:83], v[44:45], v[48:49], v[82:83]
	v_cndmask_b32_e64 v81, v91, v81, s[20:21]
	v_fma_f32 v91, -v90, v91, v88
	v_cmp_lt_f32_e64 s[20:21], 0, v91
	v_pk_fma_f32 v[54:55], v[46:47], v[78:79], v[54:55]
	v_or_b32_e32 v80, s24, v126
	v_cndmask_b32_e64 v81, v81, v90, s[20:21]
	v_mul_f32_e32 v90, 0x37800000, v81
	v_cndmask_b32_e32 v81, v81, v90, vcc
	v_cmp_class_f32_e32 vcc, v88, v181
	s_lshl_b32 s40, s22, 2
	v_add_f32_e32 v45, v69, v89
	v_cndmask_b32_e32 v81, v81, v88, vcc
	v_max_f32_e32 v81, 0x2b8cbccc, v81
	v_div_scale_f32 v88, s[20:21], v81, v81, 1.0
	v_rcp_f32_e32 v90, v88
	s_mov_b64 s[20:21], s[92:93]
	s_cmp_eq_u32 s28, 0
	s_cselect_b64 s[24:25], -1, 0
	v_fma_f32 v44, -v88, v90, 1.0
	v_fmac_f32_e32 v90, v44, v90
	v_div_scale_f32 v44, vcc, 1.0, v81, 1.0
	v_mul_f32_e32 v46, v44, v90
	v_fma_f32 v47, -v88, v46, v44
	v_fmac_f32_e32 v46, v47, v90
	v_fma_f32 v44, -v88, v46, v44
	v_div_fmas_f32 v44, v44, v90, v46
	v_div_fixup_f32 v44, v44, v81, 1.0
	v_ashrrev_i32_e32 v81, 31, v80
	v_lshlrev_b64 v[46:47], 6, v[80:81]
	s_waitcnt lgkmcnt(0)
	v_lshl_add_u64 v[46:47], s[20:21], 0, v[46:47]
	v_lshl_add_u64 v[46:47], v[46:47], 0, s[40:41]
	global_store_dword v[46:47], v45, off
	v_lshl_add_u32 v46, v146, 2, 0
	v_add_u32_e32 v69, 0x1b400, v46
	ds_read_b128 v[46:49], v69
	ds_read_b128 v[78:81], v69 offset:256
	s_lshl_b64 s[22:23], s[26:27], 8
	s_cmp_gt_u32 s28, 1
	ds_read_b128 v[88:91], v69 offset:512
	s_waitcnt lgkmcnt(2)
	v_pk_add_f32 v[48:49], v[48:49], 0 op_sel_hi:[1,0]
	s_cselect_b64 vcc, -1, 0
	v_cndmask_b32_e64 v93, v49, 0, s[24:25]
	v_cndmask_b32_e64 v92, v48, 0, s[24:25]
	s_waitcnt lgkmcnt(1)
	v_pk_add_f32 v[94:95], v[80:81], v[92:93]
	v_pk_add_f32 v[46:47], v[46:47], 0 op_sel_hi:[1,0]
	v_cndmask_b32_e32 v97, v93, v95, vcc
	v_cndmask_b32_e32 v96, v92, v94, vcc
	ds_read_b128 v[92:95], v69 offset:768
	v_cndmask_b32_e64 v101, v47, 0, s[24:25]
	v_cndmask_b32_e64 v100, v46, 0, s[24:25]
	v_pk_add_f32 v[46:47], v[46:47], v[78:79]
	v_pk_add_f32 v[78:79], v[78:79], v[100:101]
	s_cmp_eq_u32 s28, 3
	v_cndmask_b32_e32 v79, v101, v79, vcc
	v_cndmask_b32_e32 v78, v100, v78, vcc
	s_waitcnt lgkmcnt(1)
	v_pk_add_f32 v[98:99], v[90:91], v[96:97]
	s_cselect_b64 s[20:21], -1, 0
	v_pk_add_f32 v[48:49], v[48:49], v[80:81]
	v_pk_add_f32 v[80:81], v[46:47], v[88:89]
	v_pk_add_f32 v[46:47], v[88:89], v[78:79]
	v_pk_add_f32 v[48:49], v[48:49], v[90:91]
	v_cndmask_b32_e64 v89, v97, v99, s[20:21]
	v_cndmask_b32_e64 v88, v96, v98, s[20:21]
	v_cndmask_b32_e64 v79, v79, v47, s[20:21]
	v_cndmask_b32_e64 v78, v78, v46, s[20:21]
	s_waitcnt lgkmcnt(0)
	v_pk_add_f32 v[46:47], v[48:49], v[94:95]
	v_pk_add_f32 v[48:49], v[80:81], v[92:93]
	v_pk_add_f32 v[42:43], v[42:43], v[88:89]
	v_pk_add_f32 v[40:41], v[40:41], v[78:79]
	v_sub_f32_e32 v91, v46, v42
	v_sub_f32_e32 v79, v48, v40
	v_sub_f32_e32 v69, v47, v43
	v_sub_f32_e32 v89, v49, v41
	v_exp_f32_e32 v78, v40
	v_exp_f32_e64 v80, -v40
	v_sub_f32_e32 v40, v40, v154
	v_exp_f32_e32 v88, v79
	v_exp_f32_e32 v79, v41
	v_exp_f32_e64 v81, -v41
	v_sub_f32_e32 v41, v41, v155
	v_exp_f32_e32 v90, v42
	v_exp_f32_e64 v92, -v42
	v_sub_f32_e32 v42, v42, v152
	v_exp_f32_e32 v94, v91
	v_exp_f32_e32 v91, v43
	v_exp_f32_e64 v93, -v43
	v_sub_f32_e32 v43, v43, v153
	v_mul_u32_u24_e32 v45, 0x48, v126
	v_exp_f32_e32 v40, v40
	v_exp_f32_e32 v41, v41
	v_exp_f32_e32 v42, v42
	v_exp_f32_e32 v43, v43
	v_lshlrev_b32_e32 v45, 1, v45
	v_pk_mul_f32 v[84:85], v[84:85], v[44:45] op_sel_hi:[1,0]
	v_pk_mul_f32 v[86:87], v[86:87], v[44:45] op_sel_hi:[1,0]
	v_exp_f32_e32 v89, v89
	v_pk_mul_f32 v[72:73], v[72:73], v[86:87]
	v_pk_mul_f32 v[74:75], v[74:75], v[84:85]
	v_pk_mul_f32 v[66:67], v[66:67], v[90:91]
	v_pk_mul_f32 v[64:65], v[64:65], v[78:79]
	v_pk_mul_f32 v[78:79], v[76:77], v[92:93]
	v_pk_mul_f32 v[90:91], v[70:71], v[80:81]
	v_exp_f32_e32 v95, v69
	v_pk_mul_f32 v[92:93], v[74:75], v[92:93]
	v_pk_mul_f32 v[80:81], v[72:73], v[80:81]
	v_pk_mul_f32 v[42:43], v[84:85], v[42:43]
	v_pk_mul_f32 v[84:85], v[86:87], v[40:41]
	v_add3_u32 v40, 0, v45, v147
	v_cvt_pk_bf16_f32 v64, v64, v65
	v_cvt_pk_bf16_f32 v65, v66, v67
	v_cvt_pk_bf16_f32 v66, v90, v91
	v_cvt_pk_bf16_f32 v67, v78, v79
	ds_write2st64_b64 v40, v[64:65], v[66:67] offset0:72 offset1:90
	v_cvt_pk_bf16_f32 v64, v80, v81
	v_cvt_pk_bf16_f32 v65, v92, v93
	v_cvt_pk_bf16_f32 v66, v84, v85
	v_cvt_pk_bf16_f32 v67, v42, v43
	v_lshlrev_b32_e32 v102, 1, v126
	ds_write2st64_b64 v40, v[64:65], v[66:67] offset0:108 offset1:126
	v_mul_lo_u32 v64, v146, s50
	v_pk_mul_f32 v[70:71], v[70:71], v[88:89]
	v_pk_mul_f32 v[72:73], v[72:73], v[88:89]
	v_cvt_pk_bf16_f32 v41, v82, v83
	v_add3_u32 v42, s55, v102, v64
	v_add3_u32 v43, s56, v102, v64
	s_cmp_lg_u32 s28, 0
	v_pk_mul_f32 v[76:77], v[76:77], v[94:95]
	v_pk_mul_f32 v[74:75], v[74:75], v[94:95]
	v_cvt_pk_bf16_f32 v45, v54, v55
	v_cvt_pk_bf16_f32 v55, v70, v71
	v_cvt_pk_bf16_f32 v70, v72, v73
	ds_write_b16 v42, v66
	ds_write_b16_d16_hi v42, v66 offset:144
	ds_write_b16 v42, v67 offset:288
	ds_write_b16_d16_hi v42, v67 offset:432
	ds_write_b16 v43, v41
	ds_write_b16_d16_hi v43, v41 offset:144
	ds_write_b16 v43, v45 offset:288
	ds_write_b16_d16_hi v43, v45 offset:432
	v_add3_u32 v54, s57, v102, v64
	v_add3_u32 v41, s58, v102, v64
	v_cvt_pk_bf16_f32 v69, v76, v77
	v_cvt_pk_bf16_f32 v71, v74, v75
	ds_write_b16 v54, v55
	ds_write_b16_d16_hi v54, v55 offset:144
	ds_write_b16 v54, v69 offset:288
	ds_write_b16_d16_hi v54, v69 offset:432
	ds_write_b16 v41, v70
	ds_write_b16_d16_hi v41, v70 offset:144
	ds_write_b16 v41, v71 offset:288
	ds_write_b16_d16_hi v41, v71 offset:432
	s_cbranch_scc1 .LBB0_197
	s_mov_b64 s[30:31], s[94:95]
	v_exp_f32_e32 v64, v48
	v_exp_f32_e32 v65, v49
	v_exp_f32_e32 v66, v46
	v_exp_f32_e32 v67, v47
	s_waitcnt lgkmcnt(0)
	s_add_u32 s30, s30, s22
	v_ashrrev_i32_e32 v147, 31, v146
	s_addc_u32 s31, s31, s23
	v_lshl_add_u64 v[46:47], v[146:147], 2, s[30:31]
	global_store_dwordx4 v[46:47], v[64:67], off
